# SB stick-breaking loop: counted vmcnt(16) waits instead of vmcnt(0) so 2-tile-ahead K/V prefetch stays in flight
# speedup vs baseline: 1.0101x; 1.0101x over previous
; #define SBW_LOAD(j, KF, VR) do { const size_t kb_ = (size_t)(j) * 32; \
;         _Pragma("unroll") for (int s = 0; s < 4; ++s) KF[s] = *(const bf16x8*)(K + (kb_ + r32) * ld + s * 16 + hi * 8); \
;         _Pragma("unroll") for (int c4 = 0; c4 < 4; ++c4) VR[c4] = *(const u32x4*)(V + (kb_ + (lane >> 3) + 8 * c4) * ld + (lane & 7) * 8); } while (0)
; __device__ __forceinline__ void sb_wave_unit(const bf16_t* Q, const bf16_t* K, const bf16_t* V, int ld, bf16_t* O, int ldo, int q0, char* wl, int lane) {
;     ...
;     const int qpos = q0 + r32;
;     bf16x8 qf[4];
; #pragma unroll
;     for (int s = 0; s < 4; ++s) qf[s] = *(const bf16x8*)(Q + (size_t)qpos * ld + s * 16 + hi * 8);
;     f32x16 o[2]; o[0] = f32x16{}; o[1] = f32x16{};
;     float carry = 1.f;
;     ...
;     bf16x8 kfA[4], kfB[4], kfC[4]; u32x4 vrA[4], vrB[4], vrC[4];
;     int j = (q0 + 30) >> 5;
;     ...
;     SBW_LOAD(j, kfA, vrA);
;     SBW_LOAD(SBW_CL(j - 1), kfB, vrB);
.LBB0_628:
	s_lshl_b32 s0, s11, 3
	s_add_i32 s28, s7, s0
	s_lshl_b32 s39, s28, 5
	v_or_b32_e32 v234, s39, v212
	v_mad_i64_i32 v[0:1], s[0:1], v234, s78, v[228:229]
	s_ashr_i32 s29, s28, 31
	s_lshl_b64 s[0:1], s[28:29], 5
	global_load_dwordx4 v[96:99], v[0:1], off
	global_load_dwordx4 v[100:103], v[0:1], off offset:32
	global_load_dwordx4 v[104:107], v[0:1], off offset:64
	global_load_dwordx4 v[108:111], v[0:1], off offset:96
	v_or_b32_e32 v0, s0, v212
	v_mad_u64_u32 v[0:1], s[30:31], v0, s78, v[228:229]
	v_mad_i32_i24 v1, s1, v242, v1
	global_load_dwordx4 v[124:127], v[0:1], off offset:2048
	global_load_dwordx4 v[120:123], v[0:1], off offset:2080
	global_load_dwordx4 v[116:119], v[0:1], off offset:2112
	global_load_dwordx4 v[112:115], v[0:1], off offset:2144
	v_or_b32_e32 v0, s0, v214
	v_mad_u64_u32 v[0:1], s[30:31], v0, s78, v[230:231]
	v_or_b32_e32 v2, s0, v216
	v_mad_i32_i24 v1, s1, v242, v1
	v_mad_u64_u32 v[2:3], s[30:31], v2, s78, v[230:231]
	v_mad_i32_i24 v3, s1, v242, v3
	global_load_dwordx4 v[132:135], v[0:1], off
	global_load_dwordx4 v[140:143], v[2:3], off
	v_or_b32_e32 v0, s0, v218
	v_or_b32_e32 v2, s0, v220
	s_max_i32 s0, s28, 1
	v_mad_u64_u32 v[0:1], s[30:31], v0, s78, v[230:231]
	v_mad_u64_u32 v[2:3], s[30:31], v2, s78, v[230:231]
	s_add_i32 s18, s0, -1
	v_mad_i32_i24 v1, s1, v242, v1
	v_mad_i32_i24 v3, s1, v242, v3
	s_lshl_b64 s[0:1], s[18:19], 5
	global_load_dwordx4 v[152:155], v[0:1], off
	global_load_dwordx4 v[148:151], v[2:3], off
	v_or_b32_e32 v0, s0, v212
	v_mad_u64_u32 v[0:1], s[30:31], v0, s78, v[228:229]
	v_mad_u32_u24 v1, s1, v242, v1
	global_load_dwordx4 v[156:159], v[0:1], off offset:2048
	global_load_dwordx4 v[144:147], v[0:1], off offset:2080
	global_load_dwordx4 v[136:139], v[0:1], off offset:2112
	global_load_dwordx4 v[128:131], v[0:1], off offset:2144
	v_or_b32_e32 v0, s0, v214
	v_mad_u64_u32 v[0:1], s[30:31], v0, s78, v[230:231]
	v_or_b32_e32 v2, s0, v216
	v_mad_u32_u24 v1, s1, v242, v1
	v_mad_u64_u32 v[2:3], s[30:31], v2, s78, v[230:231]
	v_mad_u32_u24 v3, s1, v242, v3
	global_load_dwordx4 v[164:167], v[0:1], off
	global_load_dwordx4 v[160:163], v[2:3], off
	v_or_b32_e32 v0, s0, v218
	v_mad_u64_u32 v[0:1], s[30:31], v0, s78, v[230:231]
	v_or_b32_e32 v2, s0, v220
	v_mad_u32_u24 v1, s1, v242, v1
	v_mad_u64_u32 v[2:3], s[30:31], v2, s78, v[230:231]
	v_mad_u32_u24 v3, s1, v242, v3
	global_load_dwordx4 v[172:175], v[0:1], off
	global_load_dwordx4 v[168:171], v[2:3], off
	v_mov_b32_e32 v32, 0
	v_ashrrev_i32_e32 v235, 31, v234
	v_mov_b32_e32 v237, 1.0
	s_mov_b32 s48, s8
	s_mov_b32 s29, s37
	v_mov_b32_e32 v33, v32
	v_mov_b32_e32 v34, v32
	v_mov_b32_e32 v35, v32
	v_mov_b32_e32 v36, v32
	v_mov_b32_e32 v37, v32
	v_mov_b32_e32 v38, v32
	v_mov_b32_e32 v39, v32
	s_waitcnt vmcnt(8)
	v_mov_b32_e32 v40, v32
	v_mov_b32_e32 v41, v32
	v_mov_b32_e32 v42, v32
	v_mov_b32_e32 v43, v32
	v_mov_b32_e32 v44, v32
	v_mov_b32_e32 v45, v32
	v_mov_b32_e32 v46, v32
	v_mov_b32_e32 v47, v32
	v_mov_b32_e32 v48, v32
	v_mov_b32_e32 v49, v32
	v_mov_b32_e32 v50, v32
	v_mov_b32_e32 v51, v32
	v_mov_b32_e32 v52, v32
	v_mov_b32_e32 v53, v32
	v_mov_b32_e32 v54, v32
	v_mov_b32_e32 v55, v32
	v_mov_b32_e32 v56, v32
	v_mov_b32_e32 v57, v32
	v_mov_b32_e32 v58, v32
	v_mov_b32_e32 v59, v32
	v_mov_b32_e32 v60, v32
	v_mov_b32_e32 v61, v32
	v_mov_b32_e32 v62, v32
	v_mov_b32_e32 v63, v32
	s_branch .LBB0_632

.LBB0_632:
	s_add_i32 s0, s29, 6
	s_max_i32 s18, s0, 0
	s_lshl_b64 s[0:1], s[18:19], 5
	v_or_b32_e32 v0, s0, v212
	v_mad_u64_u32 v[0:1], s[30:31], v0, s78, v[228:229]
	v_mad_u32_u24 v1, s1, v242, v1
	global_load_dwordx4 v[188:191], v[0:1], off offset:2048
	global_load_dwordx4 v[184:187], v[0:1], off offset:2080
	global_load_dwordx4 v[180:183], v[0:1], off offset:2112
	global_load_dwordx4 v[176:179], v[0:1], off offset:2144
	v_or_b32_e32 v0, s0, v214
	v_mad_u64_u32 v[16:17], s[30:31], v0, s78, v[230:231]
	v_or_b32_e32 v18, s0, v216
	v_mad_u32_u24 v17, s1, v242, v17
	v_mad_u64_u32 v[18:19], s[30:31], v18, s78, v[230:231]
	v_mad_u32_u24 v19, s1, v242, v19
	global_load_dwordx4 v[192:195], v[16:17], off
	global_load_dwordx4 v[196:199], v[18:19], off
	v_or_b32_e32 v16, s0, v218
	v_mad_u64_u32 v[16:17], s[30:31], v16, s78, v[230:231]
	v_or_b32_e32 v18, s0, v220
	v_mad_u32_u24 v17, s1, v242, v17
	v_mad_u64_u32 v[18:19], s[30:31], v18, s78, v[230:231]
	v_mad_u32_u24 v19, s1, v242, v19
	global_load_dwordx4 v[204:207], v[16:17], off
	global_load_dwordx4 v[200:203], v[18:19], off
	s_waitcnt vmcnt(16)
	v_mfma_f32_32x32x16_bf16 v[0:15], v[124:127], v[96:99], 0
	s_waitcnt lgkmcnt(0)
	s_add_i32 s82, s36, s48
	s_add_i32 s0, s82, 0x11f
	s_cmp_lt_i32 s0, s39
	ds_write_b128 v211, v[132:135]
	ds_write_b128 v211, v[140:143] offset:512
	ds_write_b128 v211, v[152:155] offset:1024
	ds_write_b128 v211, v[148:151] offset:1536
	v_mfma_f32_32x32x16_bf16 v[0:15], v[120:123], v[100:103], v[0:15]
	v_mfma_f32_32x32x16_bf16 v[0:15], v[116:119], v[104:107], v[0:15]
	v_mfma_f32_32x32x16_bf16 v[0:15], v[112:115], v[108:111], v[0:15]
	s_nop 11
	v_mul_f32_e32 v12, 0xbe38aa3b, v12
	v_min_f32_e32 v12, 0x42c80000, v12
	v_mul_f32_e32 v0, 0xbe38aa3b, v0
	v_mul_f32_e32 v2, 0xbe38aa3b, v2
	v_mul_f32_e32 v4, 0xbe38aa3b, v4
	v_mul_f32_e32 v6, 0xbe38aa3b, v6
	v_mul_f32_e32 v8, 0xbe38aa3b, v8
	v_mul_f32_e32 v10, 0xbe38aa3b, v10
	v_exp_f32_e32 v64, v12
	v_mul_f32_e32 v12, 0xbe38aa3b, v13
	v_mul_f32_e32 v13, 0xbe38aa3b, v14
	v_min_f32_e32 v0, 0x42c80000, v0
	v_min_f32_e32 v2, 0x42c80000, v2
	v_min_f32_e32 v4, 0x42c80000, v4
	v_min_f32_e32 v6, 0x42c80000, v6
	v_min_f32_e32 v8, 0x42c80000, v8
	v_min_f32_e32 v10, 0x42c80000, v10
	v_min_f32_e32 v12, 0x42c80000, v12
	v_min_f32_e32 v13, 0x42c80000, v13
	v_exp_f32_e32 v16, v0
	v_mul_f32_e32 v0, 0xbe38aa3b, v1
	v_exp_f32_e32 v18, v2
	v_mul_f32_e32 v2, 0xbe38aa3b, v3
	v_exp_f32_e32 v22, v4
	v_mul_f32_e32 v4, 0xbe38aa3b, v5
	v_exp_f32_e32 v24, v6
	v_mul_f32_e32 v6, 0xbe38aa3b, v7
	v_exp_f32_e32 v28, v8
	v_mul_f32_e32 v8, 0xbe38aa3b, v9
	v_exp_f32_e32 v30, v10
	v_mul_f32_e32 v10, 0xbe38aa3b, v11
	v_exp_f32_e32 v65, v12
	v_exp_f32_e32 v66, v13
	v_mul_f32_e32 v13, 0xbe38aa3b, v15
	v_min_f32_e32 v0, 0x42c80000, v0
	v_min_f32_e32 v2, 0x42c80000, v2
	v_min_f32_e32 v4, 0x42c80000, v4
	v_min_f32_e32 v6, 0x42c80000, v6
	v_min_f32_e32 v8, 0x42c80000, v8
	v_min_f32_e32 v10, 0x42c80000, v10
	v_min_f32_e32 v13, 0x42c80000, v13
	v_exp_f32_e32 v17, v0
	v_exp_f32_e32 v19, v2
	v_exp_f32_e32 v23, v4
	v_exp_f32_e32 v25, v6
	v_exp_f32_e32 v29, v8
	v_exp_f32_e32 v31, v10
	v_exp_f32_e32 v67, v13
	v_add_f32_e32 v12, 1.0, v64
	v_rcp_f32_e32 v20, v12
	v_add_f32_e32 v12, 1.0, v65
	v_rcp_f32_e32 v21, v12
	v_add_f32_e32 v12, 1.0, v66
	v_add_f32_e32 v0, 1.0, v16
	v_add_f32_e32 v1, 1.0, v17
	v_add_f32_e32 v2, 1.0, v18
	v_add_f32_e32 v3, 1.0, v19
	v_add_f32_e32 v4, 1.0, v22
	v_add_f32_e32 v5, 1.0, v23
	v_add_f32_e32 v6, 1.0, v24
	v_add_f32_e32 v7, 1.0, v25
	v_add_f32_e32 v8, 1.0, v28
	v_add_f32_e32 v9, 1.0, v29
	v_add_f32_e32 v10, 1.0, v30
	v_add_f32_e32 v11, 1.0, v31
	v_rcp_f32_e32 v26, v12
	v_add_f32_e32 v12, 1.0, v67
	v_rcp_f32_e32 v0, v0
	v_rcp_f32_e32 v1, v1
	v_rcp_f32_e32 v2, v2
	v_rcp_f32_e32 v3, v3
	v_rcp_f32_e32 v4, v4
	v_rcp_f32_e32 v5, v5
	v_rcp_f32_e32 v6, v6
	v_rcp_f32_e32 v7, v7
	v_rcp_f32_e32 v8, v8
	v_rcp_f32_e32 v9, v9
	v_rcp_f32_e32 v10, v10
	v_rcp_f32_e32 v11, v11
	v_rcp_f32_e32 v27, v12
	v_pk_mul_f32 v[12:13], v[16:17], v[0:1]
	v_pk_mul_f32 v[14:15], v[18:19], v[2:3]
	v_pk_mul_f32 v[16:17], v[22:23], v[4:5]
	v_pk_mul_f32 v[18:19], v[24:25], v[6:7]
	v_pk_mul_f32 v[22:23], v[28:29], v[8:9]
	v_pk_mul_f32 v[24:25], v[30:31], v[10:11]
	v_pk_mul_f32 v[28:29], v[64:65], v[20:21]
	v_pk_mul_f32 v[30:31], v[66:67], v[26:27]
	s_cbranch_scc1 .LBB0_634
	v_add_u32_e32 v64, s48, v215
	v_add_u32_e32 v65, 0x100, v64
	v_cmp_lt_i32_e32 vcc, v65, v234
	v_add_u32_e32 v65, 0x101, v64
	v_cmp_lt_i32_e64 s[0:1], v65, v234
	v_add_u32_e32 v65, 0x102, v64
	v_cmp_lt_i32_e64 s[42:43], v65, v234
	v_add_u32_e32 v65, 0x103, v64
	v_cmp_lt_i32_e64 s[44:45], v65, v234
	v_add_u32_e32 v65, 0x108, v64
	v_cmp_lt_i32_e64 s[50:51], v65, v234
	v_add_u32_e32 v65, 0x109, v64
	v_cmp_lt_i32_e64 s[52:53], v65, v234
	v_add_u32_e32 v65, 0x10a, v64
	v_cmp_lt_i32_e64 s[54:55], v65, v234
	v_add_u32_e32 v65, 0x10b, v64
	v_cmp_lt_i32_e64 s[56:57], v65, v234
	v_add_u32_e32 v65, 0x110, v64
	v_cmp_lt_i32_e64 s[58:59], v65, v234
	v_add_u32_e32 v65, 0x111, v64
	v_cmp_lt_i32_e64 s[60:61], v65, v234
	v_add_u32_e32 v65, 0x112, v64
	v_cmp_lt_i32_e64 s[62:63], v65, v234
	v_add_u32_e32 v65, 0x113, v64
	v_cmp_lt_i32_e64 s[64:65], v65, v234
	v_add_u32_e32 v65, 0x118, v64
	v_cmp_lt_i32_e64 s[66:67], v65, v234
	v_add_u32_e32 v65, 0x119, v64
	v_cmp_lt_i32_e64 s[68:69], v65, v234
	v_add_u32_e32 v65, 0x11a, v64
	v_add_u32_e32 v64, 0x11b, v64
	v_cmp_lt_i32_e64 s[70:71], v65, v234
	v_cmp_lt_i32_e64 s[72:73], v64, v234
	s_or_b64 s[70:71], s[72:73], s[70:71]
	s_or_b64 s[68:69], s[70:71], s[68:69]
	s_or_b64 s[66:67], s[68:69], s[66:67]
	s_or_b64 s[64:65], s[66:67], s[64:65]
	s_or_b64 s[62:63], s[64:65], s[62:63]
	s_or_b64 s[60:61], s[62:63], s[60:61]
	s_or_b64 s[58:59], s[60:61], s[58:59]
	s_or_b64 s[56:57], s[58:59], s[56:57]
	s_or_b64 s[54:55], s[56:57], s[54:55]
	s_or_b64 s[52:53], s[54:55], s[52:53]
	s_or_b64 s[50:51], s[52:53], s[50:51]
	s_or_b64 s[44:45], s[50:51], s[44:45]
	s_or_b64 s[42:43], s[44:45], s[42:43]
	s_or_b64 s[0:1], s[42:43], s[0:1]
	s_or_b64 vcc, s[0:1], vcc
	v_cndmask_b32_e64 v27, 0, v27, s[72:73]
	v_cndmask_b32_e64 v26, 0, v26, s[70:71]
	v_cndmask_b32_e64 v21, 0, v21, s[68:69]
	v_cndmask_b32_e64 v20, 0, v20, s[66:67]
	v_cndmask_b32_e64 v11, 0, v11, s[64:65]
	v_cndmask_b32_e64 v10, 0, v10, s[62:63]
	v_cndmask_b32_e64 v9, 0, v9, s[60:61]
	v_cndmask_b32_e64 v8, 0, v8, s[58:59]
	v_cndmask_b32_e64 v7, 0, v7, s[56:57]
	v_cndmask_b32_e64 v6, 0, v6, s[54:55]
	v_cndmask_b32_e64 v5, 0, v5, s[52:53]
	v_cndmask_b32_e64 v4, 0, v4, s[50:51]
	v_cndmask_b32_e64 v3, 0, v3, s[44:45]
	v_cndmask_b32_e64 v2, 0, v2, s[42:43]
	v_cndmask_b32_e64 v1, 0, v1, s[0:1]
	v_cndmask_b32_e32 v0, 0, v0, vcc
	v_cndmask_b32_e32 v12, 1.0, v12, vcc
	v_cndmask_b32_e64 v13, 1.0, v13, s[0:1]
	v_cndmask_b32_e64 v14, 1.0, v14, s[42:43]
	v_cndmask_b32_e64 v15, 1.0, v15, s[44:45]
	v_cndmask_b32_e64 v16, 1.0, v16, s[50:51]
	v_cndmask_b32_e64 v17, 1.0, v17, s[52:53]
	v_cndmask_b32_e64 v18, 1.0, v18, s[54:55]
	v_cndmask_b32_e64 v19, 1.0, v19, s[56:57]
	v_cndmask_b32_e64 v22, 1.0, v22, s[58:59]
	v_cndmask_b32_e64 v23, 1.0, v23, s[60:61]
	v_cndmask_b32_e64 v24, 1.0, v24, s[62:63]
	v_cndmask_b32_e64 v25, 1.0, v25, s[64:65]
	v_cndmask_b32_e64 v28, 1.0, v28, s[66:67]
	v_cndmask_b32_e64 v29, 1.0, v29, s[68:69]
	v_cndmask_b32_e64 v30, 1.0, v30, s[70:71]
	v_cndmask_b32_e64 v31, 1.0, v31, s[72:73]
.LBB0_634:
	v_mov_b32_e32 v64, v13
	v_mov_b32_e32 v65, v14
	v_mov_b32_e32 v66, v12
	v_mov_b32_e32 v67, v15
	v_pk_mul_f32 v[64:65], v[64:65], v[66:67]
	v_mov_b32_e32 v66, v17
	v_mov_b32_e32 v67, v18
	v_mov_b32_e32 v68, v16
	v_mov_b32_e32 v69, v19
	v_pk_mul_f32 v[66:67], v[66:67], v[68:69]
	v_mov_b32_e32 v68, v23
	v_mov_b32_e32 v69, v24
	v_mov_b32_e32 v70, v22
	v_mov_b32_e32 v71, v25
	v_mul_f32_e32 v64, v64, v65
	v_pk_mul_f32 v[68:69], v[68:69], v[70:71]
	v_mov_b32_e32 v70, v29
	v_mov_b32_e32 v71, v30
	v_mov_b32_e32 v72, v28
	v_mov_b32_e32 v73, v31
	v_pk_mul_f32 v[70:71], v[70:71], v[72:73]
	v_mov_b32_e32 v12, v64
	v_mov_b32_e32 v16, v64
	v_pk_mul_f32 v[70:71], v[70:71], v[70:71] op_sel:[0,1] op_sel_hi:[1,0]
	s_nop 0
	v_permlane32_swap_b32_e32 v12, v16
	v_cndmask_b32_e64 v65, v12, v16, s[40:41]
	v_mov_b32_e32 v12, v70
	v_mov_b32_e32 v16, v70
	s_nop 1
	v_permlane32_swap_b32_e32 v12, v16
	v_cndmask_b32_e64 v71, v12, v16, s[40:41]
	v_cndmask_b32_e64 v12, 1.0, v71, s[40:41]
	v_mul_f32_e32 v12, v237, v12
	v_mul_f32_e32 v16, v31, v12
	v_mul_f32_e32 v22, v30, v16
	v_mul_f32_e32 v28, v29, v22
	v_mul_f32_e32 v12, v27, v12
	v_mul_f32_e32 v22, v21, v22
	v_mul_f32_e32 v27, v20, v28
	v_mov_b32_e32 v20, v68
	v_mov_b32_e32 v21, v70
	v_mov_b32_e32 v70, v69
	v_pk_mul_f32 v[20:21], v[20:21], v[70:71]
	v_mul_f32_e32 v26, v26, v16
	v_mov_b32_e32 v16, v20
	v_mov_b32_e32 v28, v20
	s_nop 1
	v_permlane32_swap_b32_e32 v16, v28
	v_cndmask_b32_e64 v236, v16, v28, s[40:41]
	v_cndmask_b32_e64 v16, 1.0, v236, s[40:41]
	v_pk_mul_f32 v[20:21], v[20:21], v[236:237]
	s_add_i32 s77, s29, 8
	v_mul_f32_e32 v16, v16, v21
	v_mul_f32_e32 v25, v25, v16
	v_mul_f32_e32 v24, v24, v25
	v_mul_f32_e32 v23, v23, v24
	v_mul_f32_e32 v24, v9, v24
	v_mul_f32_e32 v23, v8, v23
	v_mov_b32_e32 v8, v66
	v_mov_b32_e32 v9, v20
	v_mov_b32_e32 v20, v67
	v_pk_mul_f32 v[8:9], v[8:9], v[20:21]
	v_mul_f32_e32 v11, v11, v16
	v_mov_b32_e32 v16, v8
	v_mov_b32_e32 v20, v8
	s_nop 1
	v_permlane32_swap_b32_e32 v16, v20
	v_cndmask_b32_e64 v16, v16, v20, s[40:41]
	v_mul_f32_e32 v8, v8, v16
	v_cndmask_b32_e64 v20, 1.0, v16, s[40:41]
	v_mul_f32_e32 v66, v8, v9
	v_cndmask_b32_e64 v8, 1.0, v65, s[40:41]
	v_mul_f32_e32 v20, v20, v9
	v_mul_f32_e32 v8, v8, v66
	v_mul_f32_e32 v19, v19, v20
	v_mul_f32_e32 v9, v15, v8
	v_mul_f32_e32 v18, v18, v19
	v_mul_f32_e32 v14, v14, v9
	v_mul_f32_e32 v17, v17, v18
	v_mul_f32_e32 v13, v13, v14
	v_mul_f32_e32 v10, v10, v25
	v_mul_f32_e32 v7, v7, v20
	v_mul_f32_e32 v6, v6, v19
	v_mul_f32_e32 v5, v5, v18
	v_mul_f32_e32 v4, v4, v17
	v_mul_f32_e32 v3, v3, v8
	v_mul_f32_e32 v2, v2, v9
	v_mul_f32_e32 v1, v1, v14
	v_mul_f32_e32 v0, v0, v13
	v_cvt_pk_bf16_f32 v16, v0, v1
	v_cvt_pk_bf16_f32 v17, v2, v3
	v_cvt_pk_bf16_f32 v18, v4, v5
	v_cvt_pk_bf16_f32 v19, v6, v7
	v_cvt_pk_bf16_f32 v68, v23, v24
	v_cvt_pk_bf16_f32 v69, v10, v11
	v_cvt_pk_bf16_f32 v70, v27, v22
	v_cvt_pk_bf16_f32 v71, v26, v12
	s_waitcnt lgkmcnt(0)
; __device__ __forceinline__ s16x4 vtr(lds_cptr p) { return __builtin_bit_cast(s16x4, __builtin_amdgcn_ds_read_tr16_b64_v4i16((ATT_LAS s16x4*)p)); }
; __device__ __forceinline__ bf16x8 cat8(s16x4 lo, s16x4 hi) { return (bf16x8){lo[0], lo[1], lo[2], lo[3], hi[0], hi[1], hi[2], hi[3]}; }
; template <int KEYS> __device__ __forceinline__ void pv_tile(f32x16 (&o)[2], lds_cptr vbase, const bf16x8 (&pf)[KEYS / 16], int lane) {
;     const int hi = lane >> 5, li = lane & 15;
;     lds_cptr vp = vbase + (4 * hi + (li >> 2)) * 64 + ((lane >> 4) & 1) * 32 + (lane & 3) * 8;
; #pragma unroll
;     for (int d0 = 0; d0 < 2; ++d0)
; #pragma unroll
;         for (int ks = 0; ks < KEYS / 16; ++ks) {
;             const s16x4 lo = vtr(vp + d0 * (KEYS * 64) + ks * 1024), hh = vtr(vp + d0 * (KEYS * 64) + ks * 1024 + 512);
;             o[d0] = __builtin_amdgcn_mfma_f32_32x32x16_bf16(cat8(lo, hh), pf[ks], o[d0], 0, 0, 0);
;         }
	ds_read_b64_tr_b16 v[0:1], v213
	ds_read_b64_tr_b16 v[2:3], v213 offset:512
	s_waitcnt lgkmcnt(0)
	v_mfma_f32_32x32x16_bf16 v[32:47], v[0:3], v[16:19], v[32:47]
	ds_read_b64_tr_b16 v[20:21], v213 offset:1024
	ds_read_b64_tr_b16 v[22:23], v213 offset:1536
	s_cmp_lt_i32 s77, 1
	s_nop 8
	v_mov_b64_e32 v[0:1], v[32:33]
	v_mov_b64_e32 v[2:3], v[34:35]
	v_mov_b64_e32 v[4:5], v[36:37]
	v_mov_b64_e32 v[6:7], v[38:39]
	v_mov_b64_e32 v[8:9], v[40:41]
	v_mov_b64_e32 v[10:11], v[42:43]
	v_mov_b64_e32 v[12:13], v[44:45]
	v_mov_b64_e32 v[14:15], v[46:47]
	s_waitcnt lgkmcnt(0)
	s_nop 0
	v_mfma_f32_32x32x16_bf16 v[0:15], v[20:23], v[68:71], v[0:15]
	ds_read_b64_tr_b16 v[20:21], v213 offset:2048
	ds_read_b64_tr_b16 v[22:23], v213 offset:2560
	ds_read_b64_tr_b16 v[32:33], v213 offset:3072
	ds_read_b64_tr_b16 v[34:35], v213 offset:3584
	s_waitcnt lgkmcnt(2)
	v_mfma_f32_32x32x16_bf16 v[48:63], v[20:23], v[16:19], v[48:63]
	s_nop 11
	v_mov_b64_e32 v[16:17], v[48:49]
	v_mov_b64_e32 v[18:19], v[50:51]
	v_mov_b64_e32 v[20:21], v[52:53]
	v_mov_b64_e32 v[22:23], v[54:55]
	v_mov_b64_e32 v[24:25], v[56:57]
	v_mov_b64_e32 v[26:27], v[58:59]
	v_mov_b64_e32 v[28:29], v[60:61]
	v_mov_b64_e32 v[30:31], v[62:63]
	s_waitcnt lgkmcnt(0)
	s_nop 0
	v_mfma_f32_32x32x16_bf16 v[16:31], v[32:35], v[68:71], v[16:31]
	s_cbranch_scc1 .LBB0_629
	v_mul_f32_e32 v32, v64, v65
	v_mul_f32_e32 v49, v32, v66
	v_cmp_lt_f32_e32 vcc, 0, v49
	s_mov_b64 s[30:31], 0
	s_cbranch_vccz .LBB0_645
	s_add_i32 s1, s29, 5
	s_max_i32 s18, s1, 0
	s_lshl_b64 s[34:35], s[18:19], 5
	v_or_b32_e32 v32, s34, v212
	v_mad_u64_u32 v[32:33], s[42:43], v32, s78, v[228:229]
	v_mad_u32_u24 v33, s35, v242, v33
	global_load_dwordx4 v[124:127], v[32:33], off offset:2048
	global_load_dwordx4 v[120:123], v[32:33], off offset:2080
	global_load_dwordx4 v[116:119], v[32:33], off offset:2112
	global_load_dwordx4 v[112:115], v[32:33], off offset:2144
	v_or_b32_e32 v32, s34, v214
	v_mad_u64_u32 v[50:51], s[42:43], v32, s78, v[230:231]
	v_or_b32_e32 v48, s34, v216
	v_mad_u32_u24 v51, s35, v242, v51
	v_mad_u64_u32 v[52:53], s[42:43], v48, s78, v[230:231]
	v_or_b32_e32 v48, s34, v218
	v_mad_u32_u24 v53, s35, v242, v53
	global_load_dwordx4 v[132:135], v[50:51], off
	global_load_dwordx4 v[140:143], v[52:53], off
	v_mad_u64_u32 v[50:51], s[42:43], v48, s78, v[230:231]
	v_or_b32_e32 v48, s34, v220
	v_mad_u32_u24 v51, s35, v242, v51
	v_mad_u64_u32 v[52:53], s[42:43], v48, s78, v[230:231]
	v_mad_u32_u24 v53, s35, v242, v53
	global_load_dwordx4 v[152:155], v[50:51], off
	global_load_dwordx4 v[148:151], v[52:53], off
	s_waitcnt vmcnt(16)
	v_mfma_f32_32x32x16_bf16 v[32:47], v[156:159], v[96:99], 0
	s_waitcnt lgkmcnt(0)
	s_add_i32 s0, s82, 0x100
	s_cmp_le_i32 s0, s39
	ds_write_b128 v211, v[164:167]
	ds_write_b128 v211, v[160:163] offset:512
	ds_write_b128 v211, v[172:175] offset:1024
	ds_write_b128 v211, v[168:171] offset:1536
	v_mfma_f32_32x32x16_bf16 v[32:47], v[144:147], v[100:103], v[32:47]
	v_mfma_f32_32x32x16_bf16 v[32:47], v[136:139], v[104:107], v[32:47]
	v_mfma_f32_32x32x16_bf16 v[32:47], v[128:131], v[108:111], v[32:47]
	s_nop 11
	v_mul_f32_e32 v44, 0xbe38aa3b, v44
	v_min_f32_e32 v44, 0x42c80000, v44
	v_mul_f32_e32 v32, 0xbe38aa3b, v32
	v_mul_f32_e32 v34, 0xbe38aa3b, v34
	v_mul_f32_e32 v36, 0xbe38aa3b, v36
	v_mul_f32_e32 v38, 0xbe38aa3b, v38
	v_mul_f32_e32 v40, 0xbe38aa3b, v40
	v_mul_f32_e32 v42, 0xbe38aa3b, v42
	v_exp_f32_e32 v66, v44
	v_mul_f32_e32 v44, 0xbe38aa3b, v45
	v_mul_f32_e32 v45, 0xbe38aa3b, v46
	v_min_f32_e32 v32, 0x42c80000, v32
	v_min_f32_e32 v34, 0x42c80000, v34
	v_min_f32_e32 v36, 0x42c80000, v36
	v_min_f32_e32 v38, 0x42c80000, v38
	v_min_f32_e32 v40, 0x42c80000, v40
	v_min_f32_e32 v42, 0x42c80000, v42
	v_min_f32_e32 v44, 0x42c80000, v44
	v_min_f32_e32 v45, 0x42c80000, v45
	v_exp_f32_e32 v50, v32
	v_mul_f32_e32 v32, 0xbe38aa3b, v33
	v_exp_f32_e32 v52, v34
	v_mul_f32_e32 v34, 0xbe38aa3b, v35
	v_exp_f32_e32 v56, v36
	v_mul_f32_e32 v36, 0xbe38aa3b, v37
	v_exp_f32_e32 v58, v38
	v_mul_f32_e32 v38, 0xbe38aa3b, v39
	v_exp_f32_e32 v62, v40
	v_mul_f32_e32 v40, 0xbe38aa3b, v41
	v_exp_f32_e32 v64, v42
	v_mul_f32_e32 v42, 0xbe38aa3b, v43
	v_exp_f32_e32 v67, v44
	v_exp_f32_e32 v68, v45
	v_mul_f32_e32 v45, 0xbe38aa3b, v47
	v_min_f32_e32 v32, 0x42c80000, v32
	v_min_f32_e32 v34, 0x42c80000, v34
	v_min_f32_e32 v36, 0x42c80000, v36
	v_min_f32_e32 v38, 0x42c80000, v38
	v_min_f32_e32 v40, 0x42c80000, v40
	v_min_f32_e32 v42, 0x42c80000, v42
	v_min_f32_e32 v45, 0x42c80000, v45
	v_exp_f32_e32 v51, v32
	v_exp_f32_e32 v53, v34
	v_exp_f32_e32 v57, v36
	v_exp_f32_e32 v59, v38
	v_exp_f32_e32 v63, v40
	v_exp_f32_e32 v65, v42
	v_exp_f32_e32 v69, v45
	v_add_f32_e32 v44, 1.0, v66
	v_rcp_f32_e32 v54, v44
	v_add_f32_e32 v44, 1.0, v67
	v_rcp_f32_e32 v55, v44
	v_add_f32_e32 v44, 1.0, v68
	v_add_f32_e32 v32, 1.0, v50
	v_add_f32_e32 v33, 1.0, v51
	v_add_f32_e32 v34, 1.0, v52
	v_add_f32_e32 v35, 1.0, v53
	v_add_f32_e32 v36, 1.0, v56
	v_add_f32_e32 v37, 1.0, v57
	v_add_f32_e32 v38, 1.0, v58
	v_add_f32_e32 v39, 1.0, v59
	v_add_f32_e32 v40, 1.0, v62
	v_add_f32_e32 v41, 1.0, v63
	v_add_f32_e32 v42, 1.0, v64
	v_add_f32_e32 v43, 1.0, v65
	v_rcp_f32_e32 v60, v44
	v_add_f32_e32 v44, 1.0, v69
	v_rcp_f32_e32 v32, v32
	v_rcp_f32_e32 v33, v33
	v_rcp_f32_e32 v34, v34
	v_rcp_f32_e32 v35, v35
	v_rcp_f32_e32 v36, v36
	v_rcp_f32_e32 v37, v37
	v_rcp_f32_e32 v38, v38
	v_rcp_f32_e32 v39, v39
	v_rcp_f32_e32 v40, v40
	v_rcp_f32_e32 v41, v41
	v_rcp_f32_e32 v42, v42
	v_rcp_f32_e32 v43, v43
	v_rcp_f32_e32 v61, v44
	v_pk_mul_f32 v[44:45], v[50:51], v[32:33]
	v_pk_mul_f32 v[46:47], v[52:53], v[34:35]
	v_pk_mul_f32 v[50:51], v[56:57], v[36:37]
	v_pk_mul_f32 v[52:53], v[58:59], v[38:39]
	v_pk_mul_f32 v[56:57], v[62:63], v[40:41]
	v_pk_mul_f32 v[58:59], v[64:65], v[42:43]
	v_pk_mul_f32 v[62:63], v[66:67], v[54:55]
	v_pk_mul_f32 v[64:65], v[68:69], v[60:61]
	s_cbranch_scc1 .LBB0_638
; __device__ __forceinline__ s16x4 vtr(lds_cptr p) { return __builtin_bit_cast(s16x4, __builtin_amdgcn_ds_read_tr16_b64_v4i16((ATT_LAS s16x4*)p)); }
; __device__ __forceinline__ bf16x8 cat8(s16x4 lo, s16x4 hi) { return (bf16x8){lo[0], lo[1], lo[2], lo[3], hi[0], hi[1], hi[2], hi[3]}; }
; template <int KEYS> __device__ __forceinline__ void pv_tile(f32x16 (&o)[2], lds_cptr vbase, const bf16x8 (&pf)[KEYS / 16], int lane) {
;     const int hi = lane >> 5, li = lane & 15;
;     lds_cptr vp = vbase + (4 * hi + (li >> 2)) * 64 + ((lane >> 4) & 1) * 32 + (lane & 3) * 8;
; #pragma unroll
;     for (int d0 = 0; d0 < 2; ++d0)
; #pragma unroll
;         for (int ks = 0; ks < KEYS / 16; ++ks) {
;             const s16x4 lo = vtr(vp + d0 * (KEYS * 64) + ks * 1024), hh = vtr(vp + d0 * (KEYS * 64) + ks * 1024 + 512);
;             o[d0] = __builtin_amdgcn_mfma_f32_32x32x16_bf16(cat8(lo, hh), pf[ks], o[d0], 0, 0, 0);
;         }
	v_add_u32_e32 v48, s48, v215
	v_add_u32_e32 v66, 0xe0, v48
	v_cmp_lt_i32_e32 vcc, v66, v234
	v_add_u32_e32 v66, 0xe1, v48
	v_cmp_lt_i32_e64 s[0:1], v66, v234
	v_add_u32_e32 v66, 0xe2, v48
	v_cmp_lt_i32_e64 s[42:43], v66, v234
	v_add_u32_e32 v66, 0xe3, v48
	v_cmp_lt_i32_e64 s[44:45], v66, v234
	v_add_u32_e32 v66, 0xe8, v48
	v_cmp_lt_i32_e64 s[50:51], v66, v234
	v_add_u32_e32 v66, 0xe9, v48
	v_cmp_lt_i32_e64 s[52:53], v66, v234
	v_add_u32_e32 v66, 0xea, v48
	v_cmp_lt_i32_e64 s[54:55], v66, v234
	v_add_u32_e32 v66, 0xeb, v48
	v_cmp_lt_i32_e64 s[56:57], v66, v234
	v_add_u32_e32 v66, 0xf0, v48
	v_cmp_lt_i32_e64 s[58:59], v66, v234
	v_add_u32_e32 v66, 0xf1, v48
	v_cmp_lt_i32_e64 s[60:61], v66, v234
	v_add_u32_e32 v66, 0xf2, v48
	v_cmp_lt_i32_e64 s[62:63], v66, v234
	v_add_u32_e32 v66, 0xf3, v48
	v_cmp_lt_i32_e64 s[64:65], v66, v234
	v_add_u32_e32 v66, 0xf8, v48
	v_cmp_lt_i32_e64 s[66:67], v66, v234
	v_add_u32_e32 v66, 0xf9, v48
	v_cmp_lt_i32_e64 s[68:69], v66, v234
	v_add_u32_e32 v66, 0xfa, v48
	v_add_u32_e32 v48, 0xfb, v48
	v_cmp_lt_i32_e64 s[70:71], v66, v234
	v_cmp_lt_i32_e64 s[72:73], v48, v234
	s_or_b64 s[70:71], s[72:73], s[70:71]
	s_or_b64 s[68:69], s[70:71], s[68:69]
	s_or_b64 s[66:67], s[68:69], s[66:67]
	s_or_b64 s[64:65], s[66:67], s[64:65]
	s_or_b64 s[62:63], s[64:65], s[62:63]
	s_or_b64 s[60:61], s[62:63], s[60:61]
	s_or_b64 s[58:59], s[60:61], s[58:59]
	s_or_b64 s[56:57], s[58:59], s[56:57]
	s_or_b64 s[54:55], s[56:57], s[54:55]
	s_or_b64 s[52:53], s[54:55], s[52:53]
	s_or_b64 s[50:51], s[52:53], s[50:51]
	s_or_b64 s[44:45], s[50:51], s[44:45]
	s_or_b64 s[42:43], s[44:45], s[42:43]
	s_or_b64 s[0:1], s[42:43], s[0:1]
	s_or_b64 vcc, s[0:1], vcc
	v_cndmask_b32_e64 v61, 0, v61, s[72:73]
	v_cndmask_b32_e64 v60, 0, v60, s[70:71]
	v_cndmask_b32_e64 v55, 0, v55, s[68:69]
	v_cndmask_b32_e64 v54, 0, v54, s[66:67]
	v_cndmask_b32_e64 v43, 0, v43, s[64:65]
	v_cndmask_b32_e64 v42, 0, v42, s[62:63]
	v_cndmask_b32_e64 v41, 0, v41, s[60:61]
	v_cndmask_b32_e64 v40, 0, v40, s[58:59]
	v_cndmask_b32_e64 v39, 0, v39, s[56:57]
	v_cndmask_b32_e64 v38, 0, v38, s[54:55]
	v_cndmask_b32_e64 v37, 0, v37, s[52:53]
	v_cndmask_b32_e64 v36, 0, v36, s[50:51]
	v_cndmask_b32_e64 v35, 0, v35, s[44:45]
	v_cndmask_b32_e64 v34, 0, v34, s[42:43]
	v_cndmask_b32_e64 v33, 0, v33, s[0:1]
	v_cndmask_b32_e32 v32, 0, v32, vcc
	v_cndmask_b32_e32 v44, 1.0, v44, vcc
	v_cndmask_b32_e64 v45, 1.0, v45, s[0:1]
	v_cndmask_b32_e64 v46, 1.0, v46, s[42:43]
	v_cndmask_b32_e64 v47, 1.0, v47, s[44:45]
	v_cndmask_b32_e64 v50, 1.0, v50, s[50:51]
	v_cndmask_b32_e64 v51, 1.0, v51, s[52:53]
	v_cndmask_b32_e64 v52, 1.0, v52, s[54:55]
	v_cndmask_b32_e64 v53, 1.0, v53, s[56:57]
	v_cndmask_b32_e64 v56, 1.0, v56, s[58:59]
	v_cndmask_b32_e64 v57, 1.0, v57, s[60:61]
	v_cndmask_b32_e64 v58, 1.0, v58, s[62:63]
	v_cndmask_b32_e64 v59, 1.0, v59, s[64:65]
	v_cndmask_b32_e64 v62, 1.0, v62, s[66:67]
	v_cndmask_b32_e64 v63, 1.0, v63, s[68:69]
	v_cndmask_b32_e64 v64, 1.0, v64, s[70:71]
	v_cndmask_b32_e64 v65, 1.0, v65, s[72:73]
.LBB0_638:
	v_mov_b32_e32 v66, v45
	v_mov_b32_e32 v67, v46
	v_mov_b32_e32 v68, v44
	v_mov_b32_e32 v69, v47
	v_pk_mul_f32 v[66:67], v[66:67], v[68:69]
	v_mov_b32_e32 v68, v50
	v_mul_f32_e32 v44, v66, v67
	v_mov_b32_e32 v66, v51
	v_mov_b32_e32 v67, v52
	v_mov_b32_e32 v69, v53
	v_pk_mul_f32 v[66:67], v[66:67], v[68:69]
	v_mov_b32_e32 v68, v57
	v_mov_b32_e32 v69, v58
	v_mov_b32_e32 v70, v56
	v_mov_b32_e32 v71, v59
	v_pk_mul_f32 v[68:69], v[68:69], v[70:71]
	v_mov_b32_e32 v70, v63
	v_mov_b32_e32 v71, v64
	v_mov_b32_e32 v72, v62
	v_mov_b32_e32 v73, v65
	v_pk_mul_f32 v[70:71], v[70:71], v[72:73]
	v_mov_b32_e32 v48, v44
	v_mov_b32_e32 v50, v44
	v_pk_mul_f32 v[70:71], v[70:71], v[70:71] op_sel:[0,1] op_sel_hi:[1,0]
	s_nop 0
	v_permlane32_swap_b32_e32 v48, v50
	v_cndmask_b32_e64 v50, v48, v50, s[40:41]
	v_mov_b32_e32 v48, v70
	v_mov_b32_e32 v56, v70
	s_nop 1
	v_permlane32_swap_b32_e32 v48, v56
	v_cndmask_b32_e64 v71, v48, v56, s[40:41]
	v_cndmask_b32_e64 v48, 1.0, v71, s[40:41]
	v_mul_f32_e32 v48, v49, v48
	v_mul_f32_e32 v56, v65, v48
	v_mul_f32_e32 v62, v64, v56
	v_mul_f32_e32 v63, v63, v62
	v_mul_f32_e32 v56, v60, v56
	v_mul_f32_e32 v60, v55, v62
	v_mul_f32_e32 v62, v54, v63
	v_mov_b32_e32 v54, v68
	v_mov_b32_e32 v55, v70
	v_mov_b32_e32 v70, v69
	v_pk_mul_f32 v[54:55], v[54:55], v[70:71]
	v_mul_f32_e32 v61, v61, v48
	v_mov_b32_e32 v48, v54
	v_mov_b32_e32 v63, v54
	s_nop 1
	v_permlane32_swap_b32_e32 v48, v63
	v_cndmask_b32_e64 v48, v48, v63, s[40:41]
	v_cndmask_b32_e64 v63, 1.0, v48, s[40:41]
	v_pk_mul_f32 v[48:49], v[54:55], v[48:49]
	s_mov_b64 s[44:45], -1
	v_mul_f32_e32 v54, v63, v49
	v_mul_f32_e32 v55, v59, v54
	v_mul_f32_e32 v58, v58, v55
	v_mul_f32_e32 v57, v57, v58
	v_mul_f32_e32 v43, v43, v54
	v_mul_f32_e32 v42, v42, v55
	v_mul_f32_e32 v54, v41, v58
	v_mul_f32_e32 v55, v40, v57
	v_mov_b32_e32 v40, v66
	v_mov_b32_e32 v41, v48
	v_mov_b32_e32 v48, v67
	v_pk_mul_f32 v[40:41], v[40:41], v[48:49]
	s_mov_b64 s[34:35], 0
	v_mov_b32_e32 v48, v40
	v_mov_b32_e32 v49, v40
	s_nop 1
	v_permlane32_swap_b32_e32 v48, v49
	v_cndmask_b32_e64 v48, v48, v49, s[40:41]
	v_cndmask_b32_e64 v49, 1.0, v48, s[40:41]
	v_mul_f32_e32 v49, v49, v41
	v_mul_f32_e32 v53, v53, v49
	v_mul_f32_e32 v52, v52, v53
	v_mul_f32_e32 v51, v51, v52
	v_mul_f32_e32 v39, v39, v49
	v_mul_f32_e32 v49, v36, v51
	v_mul_f32_e32 v36, v40, v48
	v_mul_f32_e32 v36, v36, v41
	v_cndmask_b32_e64 v40, 1.0, v50, s[40:41]
	v_mul_f32_e32 v40, v40, v36
	v_mul_f32_e32 v41, v47, v40
	v_mul_f32_e32 v46, v46, v41
	v_mul_f32_e32 v45, v45, v46
	v_mul_f32_e32 v38, v38, v53
	v_mul_f32_e32 v35, v35, v40
	v_mul_f32_e32 v34, v34, v41
	v_mul_f32_e32 v33, v33, v46
	v_mul_f32_e32 v32, v32, v45
	v_mul_f32_e32 v37, v37, v52
	v_cvt_pk_bf16_f32 v32, v32, v33
	v_cvt_pk_bf16_f32 v33, v34, v35
	v_cvt_pk_bf16_f32 v34, v49, v37
	v_cvt_pk_bf16_f32 v35, v38, v39
	v_cvt_pk_bf16_f32 v38, v55, v54
	v_cvt_pk_bf16_f32 v39, v42, v43
	v_cvt_pk_bf16_f32 v40, v62, v60
	v_cvt_pk_bf16_f32 v41, v56, v61
	s_waitcnt lgkmcnt(0)
	ds_read_b64_tr_b16 v[46:47], v213
	ds_read_b64_tr_b16 v[48:49], v213 offset:512
	ds_read_b64_tr_b16 v[52:53], v213 offset:1024
	ds_read_b64_tr_b16 v[54:55], v213 offset:1536
	s_waitcnt lgkmcnt(2)
	v_mfma_f32_32x32x16_bf16 v[64:79], v[46:49], v[32:35], v[0:15]
	s_cmp_eq_u32 s29, -7
	s_mov_b64 s[0:1], 0
	s_mov_b64 s[42:43], -1
	s_waitcnt lgkmcnt(0)
	v_mfma_f32_32x32x16_bf16 v[64:79], v[52:55], v[38:41], v[64:79]
	ds_read_b64_tr_b16 v[46:47], v213 offset:2048
	ds_read_b64_tr_b16 v[48:49], v213 offset:2560
	ds_read_b64_tr_b16 v[52:53], v213 offset:3072
	ds_read_b64_tr_b16 v[54:55], v213 offset:3584
	s_waitcnt lgkmcnt(2)
	v_mfma_f32_32x32x16_bf16 v[80:95], v[46:49], v[32:35], v[16:31]
	s_waitcnt lgkmcnt(0)
	v_mfma_f32_32x32x16_bf16 v[80:95], v[52:55], v[38:41], v[80:95]
	s_cbranch_scc1 .LBB0_631
; #define SBW_LOAD(j, KF, VR) do { const size_t kb_ = (size_t)(j) * 32; \
;         _Pragma("unroll") for (int s = 0; s < 4; ++s) KF[s] = *(const bf16x8*)(K + (kb_ + r32) * ld + s * 16 + hi * 8); \
;         _Pragma("unroll") for (int c4 = 0; c4 < 4; ++c4) VR[c4] = *(const u32x4*)(V + (kb_ + (lane >> 3) + 8 * c4) * ld + (lane & 7) * 8); } while (0)
; __device__ __forceinline__ void sb_wave_unit(const bf16_t* Q, const bf16_t* K, const bf16_t* V, int ld, bf16_t* O, int ldo, int q0, char* wl, int lane) {
;     ...
;         if (j < 2 || !__any(carry > 0.f)) break;
;         SBW_LOAD(SBW_CL(j - 4), kfB, vrB);
;         SBW_TILE(j - 2, kfC, vrC);
	v_mul_f32_e32 v32, v44, v50
	v_mul_f32_e32 v49, v32, v36
	v_cmp_lt_f32_e32 vcc, 0, v49
	s_cbranch_vccz .LBB0_646
	s_min_u32 s0, s28, 4
	s_sub_i32 s0, s29, s0
	s_add_i32 s18, s0, 8
	s_lshl_b64 s[0:1], s[18:19], 5
	v_or_b32_e32 v32, s0, v212
	v_mad_u64_u32 v[32:33], s[42:43], v32, s78, v[228:229]
	v_mad_u32_u24 v33, s1, v242, v33
	global_load_dwordx4 v[156:159], v[32:33], off offset:2048
	global_load_dwordx4 v[144:147], v[32:33], off offset:2080
	global_load_dwordx4 v[136:139], v[32:33], off offset:2112
	global_load_dwordx4 v[128:131], v[32:33], off offset:2144
	v_or_b32_e32 v32, s0, v214
	v_mad_u64_u32 v[50:51], s[42:43], v32, s78, v[230:231]
	v_or_b32_e32 v48, s0, v216
	v_mad_u32_u24 v51, s1, v242, v51
	v_mad_u64_u32 v[52:53], s[42:43], v48, s78, v[230:231]
	v_or_b32_e32 v48, s0, v218
	v_mad_u32_u24 v53, s1, v242, v53
	global_load_dwordx4 v[164:167], v[50:51], off
	global_load_dwordx4 v[160:163], v[52:53], off
	v_mad_u64_u32 v[50:51], s[42:43], v48, s78, v[230:231]
	v_or_b32_e32 v48, s0, v220
	v_mad_u32_u24 v51, s1, v242, v51
	v_mad_u64_u32 v[52:53], s[42:43], v48, s78, v[230:231]
	v_mad_u32_u24 v53, s1, v242, v53
	global_load_dwordx4 v[172:175], v[50:51], off
	global_load_dwordx4 v[168:171], v[52:53], off
	s_waitcnt vmcnt(16)
	v_mfma_f32_32x32x16_bf16 v[32:47], v[188:191], v[96:99], 0
	s_waitcnt lgkmcnt(0)
	s_addk_i32 s82, 0xdf
	s_cmp_lt_i32 s82, s39
	ds_write_b128 v211, v[192:195]
	ds_write_b128 v211, v[196:199] offset:512
	ds_write_b128 v211, v[204:207] offset:1024
	ds_write_b128 v211, v[200:203] offset:1536
	v_mfma_f32_32x32x16_bf16 v[32:47], v[184:187], v[100:103], v[32:47]
	v_mfma_f32_32x32x16_bf16 v[32:47], v[180:183], v[104:107], v[32:47]
	v_mfma_f32_32x32x16_bf16 v[32:47], v[176:179], v[108:111], v[32:47]
	s_nop 11
	v_mul_f32_e32 v44, 0xbe38aa3b, v44
	v_min_f32_e32 v44, 0x42c80000, v44
	v_mul_f32_e32 v32, 0xbe38aa3b, v32
	v_mul_f32_e32 v34, 0xbe38aa3b, v34
	v_mul_f32_e32 v36, 0xbe38aa3b, v36
	v_mul_f32_e32 v38, 0xbe38aa3b, v38
	v_mul_f32_e32 v40, 0xbe38aa3b, v40
	v_mul_f32_e32 v42, 0xbe38aa3b, v42
	v_exp_f32_e32 v178, v44
	v_mul_f32_e32 v44, 0xbe38aa3b, v45
	v_mul_f32_e32 v45, 0xbe38aa3b, v46
	v_min_f32_e32 v32, 0x42c80000, v32
	v_min_f32_e32 v34, 0x42c80000, v34
	v_min_f32_e32 v36, 0x42c80000, v36
	v_min_f32_e32 v38, 0x42c80000, v38
	v_min_f32_e32 v40, 0x42c80000, v40
	v_min_f32_e32 v42, 0x42c80000, v42
	v_min_f32_e32 v44, 0x42c80000, v44
	v_min_f32_e32 v45, 0x42c80000, v45
	v_exp_f32_e32 v50, v32
	v_mul_f32_e32 v32, 0xbe38aa3b, v33
	v_exp_f32_e32 v52, v34
	v_mul_f32_e32 v34, 0xbe38aa3b, v35
	v_exp_f32_e32 v56, v36
	v_mul_f32_e32 v36, 0xbe38aa3b, v37
	v_exp_f32_e32 v58, v38
	v_mul_f32_e32 v38, 0xbe38aa3b, v39
	v_exp_f32_e32 v62, v40
	v_mul_f32_e32 v40, 0xbe38aa3b, v41
	v_exp_f32_e32 v176, v42
	v_mul_f32_e32 v42, 0xbe38aa3b, v43
	v_exp_f32_e32 v179, v44
	v_exp_f32_e32 v180, v45
	v_mul_f32_e32 v45, 0xbe38aa3b, v47
	v_min_f32_e32 v32, 0x42c80000, v32
	v_min_f32_e32 v34, 0x42c80000, v34
	v_min_f32_e32 v36, 0x42c80000, v36
	v_min_f32_e32 v38, 0x42c80000, v38
	v_min_f32_e32 v40, 0x42c80000, v40
	v_min_f32_e32 v42, 0x42c80000, v42
	v_min_f32_e32 v45, 0x42c80000, v45
	v_exp_f32_e32 v51, v32
	v_exp_f32_e32 v53, v34
	v_exp_f32_e32 v57, v36
	v_exp_f32_e32 v59, v38
	v_exp_f32_e32 v63, v40
	v_exp_f32_e32 v177, v42
	v_exp_f32_e32 v181, v45
	v_add_f32_e32 v44, 1.0, v178
	v_rcp_f32_e32 v54, v44
	v_add_f32_e32 v44, 1.0, v179
	v_rcp_f32_e32 v55, v44
	v_add_f32_e32 v44, 1.0, v180
	v_add_f32_e32 v32, 1.0, v50
	v_add_f32_e32 v33, 1.0, v51
	v_add_f32_e32 v34, 1.0, v52
	v_add_f32_e32 v35, 1.0, v53
	v_add_f32_e32 v36, 1.0, v56
	v_add_f32_e32 v37, 1.0, v57
	v_add_f32_e32 v38, 1.0, v58
	v_add_f32_e32 v39, 1.0, v59
	v_add_f32_e32 v40, 1.0, v62
	v_add_f32_e32 v41, 1.0, v63
	v_add_f32_e32 v42, 1.0, v176
	v_add_f32_e32 v43, 1.0, v177
	v_rcp_f32_e32 v60, v44
	v_add_f32_e32 v44, 1.0, v181
	v_rcp_f32_e32 v32, v32
	v_rcp_f32_e32 v33, v33
	v_rcp_f32_e32 v34, v34
	v_rcp_f32_e32 v35, v35
	v_rcp_f32_e32 v36, v36
	v_rcp_f32_e32 v37, v37
	v_rcp_f32_e32 v38, v38
	v_rcp_f32_e32 v39, v39
	v_rcp_f32_e32 v40, v40
	v_rcp_f32_e32 v41, v41
	v_rcp_f32_e32 v42, v42
	v_rcp_f32_e32 v43, v43
	v_rcp_f32_e32 v61, v44
	v_pk_mul_f32 v[44:45], v[50:51], v[32:33]
	v_pk_mul_f32 v[46:47], v[52:53], v[34:35]
	v_pk_mul_f32 v[50:51], v[56:57], v[36:37]
	v_pk_mul_f32 v[52:53], v[58:59], v[38:39]
	v_pk_mul_f32 v[56:57], v[62:63], v[40:41]
	v_pk_mul_f32 v[58:59], v[176:177], v[42:43]
	v_pk_mul_f32 v[62:63], v[178:179], v[54:55]
	v_pk_mul_f32 v[176:177], v[180:181], v[60:61]
	s_cbranch_scc1 .LBB0_642
	v_add_u32_e32 v48, s48, v215
	v_add_u32_e32 v178, 0xc0, v48
	v_cmp_lt_i32_e32 vcc, v178, v234
	v_add_u32_e32 v178, 0xc1, v48
	v_cmp_lt_i32_e64 s[0:1], v178, v234
	v_add_u32_e32 v178, 0xc2, v48
	v_cmp_lt_i32_e64 s[42:43], v178, v234
	v_add_u32_e32 v178, 0xc3, v48
	v_cmp_lt_i32_e64 s[44:45], v178, v234
	v_add_u32_e32 v178, 0xc8, v48
	v_cmp_lt_i32_e64 s[50:51], v178, v234
	v_add_u32_e32 v178, 0xc9, v48
	v_cmp_lt_i32_e64 s[52:53], v178, v234
	v_add_u32_e32 v178, 0xca, v48
	v_cmp_lt_i32_e64 s[54:55], v178, v234
	v_add_u32_e32 v178, 0xcb, v48
	v_cmp_lt_i32_e64 s[56:57], v178, v234
	v_add_u32_e32 v178, 0xd0, v48
	v_cmp_lt_i32_e64 s[58:59], v178, v234
	v_add_u32_e32 v178, 0xd1, v48
	v_cmp_lt_i32_e64 s[60:61], v178, v234
	v_add_u32_e32 v178, 0xd2, v48
	v_cmp_lt_i32_e64 s[62:63], v178, v234
	v_add_u32_e32 v178, 0xd3, v48
	v_cmp_lt_i32_e64 s[64:65], v178, v234
	v_add_u32_e32 v178, 0xd8, v48
	v_cmp_lt_i32_e64 s[66:67], v178, v234
	v_add_u32_e32 v178, 0xd9, v48
	v_cmp_lt_i32_e64 s[68:69], v178, v234
	v_add_u32_e32 v178, 0xda, v48
	v_add_u32_e32 v48, 0xdb, v48
	v_cmp_lt_i32_e64 s[70:71], v178, v234
	v_cmp_lt_i32_e64 s[72:73], v48, v234
	s_or_b64 s[70:71], s[72:73], s[70:71]
	s_or_b64 s[68:69], s[70:71], s[68:69]
	s_or_b64 s[66:67], s[68:69], s[66:67]
	s_or_b64 s[64:65], s[66:67], s[64:65]
	s_or_b64 s[62:63], s[64:65], s[62:63]
	s_or_b64 s[60:61], s[62:63], s[60:61]
	s_or_b64 s[58:59], s[60:61], s[58:59]
	s_or_b64 s[56:57], s[58:59], s[56:57]
	s_or_b64 s[54:55], s[56:57], s[54:55]
	s_or_b64 s[52:53], s[54:55], s[52:53]
	s_or_b64 s[50:51], s[52:53], s[50:51]
	s_or_b64 s[44:45], s[50:51], s[44:45]
	s_or_b64 s[42:43], s[44:45], s[42:43]
	s_or_b64 s[0:1], s[42:43], s[0:1]
	s_or_b64 vcc, s[0:1], vcc
	v_cndmask_b32_e64 v61, 0, v61, s[72:73]
	v_cndmask_b32_e64 v60, 0, v60, s[70:71]
	v_cndmask_b32_e64 v55, 0, v55, s[68:69]
	v_cndmask_b32_e64 v54, 0, v54, s[66:67]
	v_cndmask_b32_e64 v43, 0, v43, s[64:65]
	v_cndmask_b32_e64 v42, 0, v42, s[62:63]
	v_cndmask_b32_e64 v41, 0, v41, s[60:61]
	v_cndmask_b32_e64 v40, 0, v40, s[58:59]
	v_cndmask_b32_e64 v39, 0, v39, s[56:57]
	v_cndmask_b32_e64 v38, 0, v38, s[54:55]
	v_cndmask_b32_e64 v37, 0, v37, s[52:53]
	v_cndmask_b32_e64 v36, 0, v36, s[50:51]
	v_cndmask_b32_e64 v35, 0, v35, s[44:45]
	v_cndmask_b32_e64 v34, 0, v34, s[42:43]
	v_cndmask_b32_e64 v33, 0, v33, s[0:1]
	v_cndmask_b32_e32 v32, 0, v32, vcc
	v_cndmask_b32_e32 v44, 1.0, v44, vcc
	v_cndmask_b32_e64 v45, 1.0, v45, s[0:1]
	v_cndmask_b32_e64 v46, 1.0, v46, s[42:43]
	v_cndmask_b32_e64 v47, 1.0, v47, s[44:45]
	v_cndmask_b32_e64 v50, 1.0, v50, s[50:51]
	v_cndmask_b32_e64 v51, 1.0, v51, s[52:53]
	v_cndmask_b32_e64 v52, 1.0, v52, s[54:55]
	v_cndmask_b32_e64 v53, 1.0, v53, s[56:57]
	v_cndmask_b32_e64 v56, 1.0, v56, s[58:59]
	v_cndmask_b32_e64 v57, 1.0, v57, s[60:61]
	v_cndmask_b32_e64 v58, 1.0, v58, s[62:63]
	v_cndmask_b32_e64 v59, 1.0, v59, s[64:65]
	v_cndmask_b32_e64 v62, 1.0, v62, s[66:67]
	v_cndmask_b32_e64 v63, 1.0, v63, s[68:69]
	v_cndmask_b32_e64 v176, 1.0, v176, s[70:71]
	v_cndmask_b32_e64 v177, 1.0, v177, s[72:73]
